# stack13 + P.V stream: per-MFMA counted lgkmcnt waits for the V fragments instead of per-group lgkmcnt(0)
# baseline (speedup 1.0000x reference)
.Li0_sm:
	ds_read_b64_tr_b16 v[188:189], v158 offset:0x400
	ds_read_b64_tr_b16 v[190:191], v158 offset:0xc00
	ds_read_b64_tr_b16 v[192:193], v158 offset:0x600
	ds_read_b64_tr_b16 v[194:195], v158 offset:0xe00
	s_waitcnt lgkmcnt(6)
	v_mfma_f32_32x32x16_bf16 v[48:63], v[176:179], v[180:183], v[48:63]
	ds_read_b64_tr_b16 v[180:181], v158 offset:0x1000
	ds_read_b64_tr_b16 v[182:183], v158 offset:0x1800
	v_mul_f32_e32 v114, 0xbe0293ee, v166
	v_max_f32_e32 v112, v65, v65
	v_max_f32_e32 v113, v64, v64
	v_fmamk_f32 v64, v64, 0x3e0293ee, v114
	v_max_f32_e32 v112, v113, v112
	v_exp_f32_e32 v64, v64
	s_waitcnt lgkmcnt(6)
	v_mfma_f32_32x32x16_bf16 v[32:47], v[176:179], v[184:187], v[32:47]
	ds_read_b64_tr_b16 v[184:185], v158 offset:0x1200
	ds_read_b64_tr_b16 v[186:187], v158 offset:0x1a00
	v_fmamk_f32 v65, v65, 0x3e0293ee, v114
	v_max3_f32 v112, v112, v66, v67
	v_exp_f32_e32 v65, v65
	v_fmamk_f32 v66, v66, 0x3e0293ee, v114
	v_exp_f32_e32 v66, v66
	v_fmamk_f32 v67, v67, 0x3e0293ee, v114
	s_waitcnt lgkmcnt(6)
	v_mfma_f32_32x32x16_bf16 v[16:31], v[176:179], v[188:191], v[16:31]
	ds_read_b64_tr_b16 v[188:189], v158 offset:0x1400
	ds_read_b64_tr_b16 v[190:191], v158 offset:0x1c00
	v_max3_f32 v112, v112, v68, v69
	v_exp_f32_e32 v67, v67
	v_fmamk_f32 v68, v68, 0x3e0293ee, v114
	v_add_f32_e32 v115, 0, v64
	v_exp_f32_e32 v68, v68
	v_fmamk_f32 v69, v69, 0x3e0293ee, v114
	s_waitcnt lgkmcnt(6)
	v_mfma_f32_32x32x16_bf16 v[0:15], v[176:179], v[192:195], v[0:15]
	ds_read_b64_tr_b16 v[192:193], v158 offset:0x1600
	ds_read_b64_tr_b16 v[194:195], v158 offset:0x1e00
	v_max3_f32 v112, v112, v70, v71
	v_add_f32_e32 v115, v65, v115
	v_exp_f32_e32 v69, v69
	v_fmamk_f32 v70, v70, 0x3e0293ee, v114
	v_add_f32_e32 v115, v66, v115
	v_exp_f32_e32 v70, v70
	s_waitcnt lgkmcnt(6)
	v_mfma_f32_32x32x16_bf16 v[48:63], v[124:127], v[180:183], v[48:63]
	ds_read_b64_tr_b16 v[180:181], v158 offset:0x2000
	ds_read_b64_tr_b16 v[182:183], v158 offset:0x2800
	v_fmamk_f32 v71, v71, 0x3e0293ee, v114
	v_max3_f32 v112, v112, v72, v73
	v_add_f32_e32 v115, v67, v115
	v_exp_f32_e32 v71, v71
	v_fmamk_f32 v72, v72, 0x3e0293ee, v114
	v_add_f32_e32 v115, v68, v115
	s_waitcnt lgkmcnt(6)
	v_mfma_f32_32x32x16_bf16 v[32:47], v[124:127], v[184:187], v[32:47]
	ds_read_b64_tr_b16 v[184:185], v158 offset:0x2200
	ds_read_b64_tr_b16 v[186:187], v158 offset:0x2a00
	v_exp_f32_e32 v72, v72
	v_fmamk_f32 v73, v73, 0x3e0293ee, v114
	v_max3_f32 v112, v112, v74, v75
	v_add_f32_e32 v115, v69, v115
	v_exp_f32_e32 v73, v73
	v_fmamk_f32 v74, v74, 0x3e0293ee, v114
	s_waitcnt lgkmcnt(6)
	v_mfma_f32_32x32x16_bf16 v[16:31], v[124:127], v[188:191], v[16:31]
	ds_read_b64_tr_b16 v[188:189], v158 offset:0x2400
	ds_read_b64_tr_b16 v[190:191], v158 offset:0x2c00
	v_add_f32_e32 v115, v70, v115
	v_exp_f32_e32 v74, v74
	v_fmamk_f32 v75, v75, 0x3e0293ee, v114
	v_max3_f32 v112, v112, v76, v77
	v_add_f32_e32 v115, v71, v115
	v_exp_f32_e32 v75, v75
	s_waitcnt lgkmcnt(6)
	v_mfma_f32_32x32x16_bf16 v[0:15], v[124:127], v[192:195], v[0:15]
	ds_read_b64_tr_b16 v[192:193], v158 offset:0x2600
	ds_read_b64_tr_b16 v[194:195], v158 offset:0x2e00
	v_fmamk_f32 v76, v76, 0x3e0293ee, v114
	v_add_f32_e32 v115, v72, v115
	v_exp_f32_e32 v76, v76
	v_fmamk_f32 v77, v77, 0x3e0293ee, v114
	v_max3_f32 v112, v112, v78, v79
	v_add_f32_e32 v115, v73, v115
	s_waitcnt lgkmcnt(6)
	v_mfma_f32_32x32x16_bf16 v[48:63], v[172:175], v[180:183], v[48:63]
	ds_read_b64_tr_b16 v[180:181], v158 offset:0x3000
	ds_read_b64_tr_b16 v[182:183], v158 offset:0x3800
	v_exp_f32_e32 v77, v77
	v_fmamk_f32 v78, v78, 0x3e0293ee, v114
	v_add_f32_e32 v115, v74, v115
	v_exp_f32_e32 v78, v78
	v_fmac_f32_e32 v114, 0x3e0293ee, v79
	v_add_f32_e32 v115, v75, v115
	s_waitcnt lgkmcnt(6)
	v_mfma_f32_32x32x16_bf16 v[32:47], v[172:175], v[184:187], v[32:47]
	ds_read_b64_tr_b16 v[184:185], v158 offset:0x3200
	ds_read_b64_tr_b16 v[186:187], v158 offset:0x3a00
	v_exp_f32_e32 v79, v114
	v_add_f32_e32 v114, v76, v115
	v_mov_b32_e32 v113, v112
	v_add_f32_e32 v114, v77, v114
	s_nop 0
	v_permlane32_swap_b32_e32 v112, v113
	v_add_f32_e32 v114, v78, v114
	s_waitcnt lgkmcnt(6)
	v_mfma_f32_32x32x16_bf16 v[16:31], v[172:175], v[188:191], v[16:31]
	ds_read_b64_tr_b16 v[188:189], v158 offset:0x3400
	ds_read_b64_tr_b16 v[190:191], v158 offset:0x3c00
	v_add_f32_e32 v120, v79, v114
	v_max_f32_e32 v113, v113, v113
	v_max_f32_e32 v112, v112, v112
	v_max_f32_e32 v164, v112, v113
	v_mov_b32_e32 v121, v120
	v_cvt_pk_bf16_f32 v112, v64, v65
	s_waitcnt lgkmcnt(6)
	v_mfma_f32_32x32x16_bf16 v[0:15], v[172:175], v[192:195], v[0:15]
	ds_read_b64_tr_b16 v[192:193], v158 offset:0x3600
	ds_read_b64_tr_b16 v[194:195], v158 offset:0x3e00
	v_cvt_pk_bf16_f32 v113, v66, v67
	v_cvt_pk_bf16_f32 v114, v68, v69
	v_cvt_pk_bf16_f32 v115, v70, v71
	v_cvt_pk_bf16_f32 v116, v72, v73
	v_cvt_pk_bf16_f32 v117, v74, v75
	v_cvt_pk_bf16_f32 v118, v76, v77
	s_waitcnt lgkmcnt(6)
	v_mfma_f32_32x32x16_bf16 v[48:63], v[168:171], v[180:183], v[48:63]
	v_cvt_pk_bf16_f32 v119, v78, v79
	s_nop 1
	v_permlane32_swap_b32_e32 v120, v121
	v_permlane32_swap_b32_e32 v112, v114
	v_permlane32_swap_b32_e32 v113, v115
	v_permlane32_swap_b32_e32 v116, v118
	v_permlane32_swap_b32_e32 v117, v119
	s_waitcnt lgkmcnt(4)
	v_mfma_f32_32x32x16_bf16 v[32:47], v[168:171], v[184:187], v[32:47]
	ds_write_b128 v157, v[112:115] offset:4096
	ds_write_b128 v157, v[116:119] offset:5120
	v_add_f32_e32 v120, v120, v121
	v_add_f32_e32 v155, v155, v120
	s_waitcnt lgkmcnt(4)
	v_mfma_f32_32x32x16_bf16 v[16:31], v[168:171], v[188:191], v[16:31]
	s_waitcnt lgkmcnt(2)
	v_mfma_f32_32x32x16_bf16 v[0:15], v[168:171], v[192:195], v[0:15]
	s_and_saveexec_b64 s[52:53], s[4:5]
	ds_write_b32 v160, v164 offset:8448
	s_or_b64 exec, exec, s[52:53]
	s_waitcnt vmcnt(0)
	s_waitcnt vmcnt(0) lgkmcnt(0)
	s_barrier
	s_branch .LBB0_748

.Li1_sm:
	ds_read_b64_tr_b16 v[188:189], v158 offset:0x8400
	ds_read_b64_tr_b16 v[190:191], v158 offset:0x8c00
	ds_read_b64_tr_b16 v[192:193], v158 offset:0x8600
	ds_read_b64_tr_b16 v[194:195], v158 offset:0x8e00
	s_waitcnt lgkmcnt(6)
	v_mfma_f32_32x32x16_bf16 v[48:63], v[176:179], v[180:183], v[48:63]
	ds_read_b64_tr_b16 v[180:181], v158 offset:0x9000
	ds_read_b64_tr_b16 v[182:183], v158 offset:0x9800
	v_mul_f32_e32 v114, 0xbe0293ee, v165
	v_max_f32_e32 v112, v65, v65
	v_max_f32_e32 v113, v64, v64
	v_fmamk_f32 v64, v64, 0x3e0293ee, v114
	v_max_f32_e32 v112, v113, v112
	v_exp_f32_e32 v64, v64
	s_waitcnt lgkmcnt(6)
	v_mfma_f32_32x32x16_bf16 v[32:47], v[176:179], v[184:187], v[32:47]
	ds_read_b64_tr_b16 v[184:185], v158 offset:0x9200
	ds_read_b64_tr_b16 v[186:187], v158 offset:0x9a00
	v_fmamk_f32 v65, v65, 0x3e0293ee, v114
	v_max3_f32 v112, v112, v66, v67
	v_exp_f32_e32 v65, v65
	v_fmamk_f32 v66, v66, 0x3e0293ee, v114
	v_exp_f32_e32 v66, v66
	v_fmamk_f32 v67, v67, 0x3e0293ee, v114
	s_waitcnt lgkmcnt(6)
	v_mfma_f32_32x32x16_bf16 v[16:31], v[176:179], v[188:191], v[16:31]
	ds_read_b64_tr_b16 v[188:189], v158 offset:0x9400
	ds_read_b64_tr_b16 v[190:191], v158 offset:0x9c00
	v_max3_f32 v112, v112, v68, v69
	v_exp_f32_e32 v67, v67
	v_fmamk_f32 v68, v68, 0x3e0293ee, v114
	v_add_f32_e32 v115, 0, v64
	v_exp_f32_e32 v68, v68
	v_fmamk_f32 v69, v69, 0x3e0293ee, v114
	s_waitcnt lgkmcnt(6)
	v_mfma_f32_32x32x16_bf16 v[0:15], v[176:179], v[192:195], v[0:15]
	ds_read_b64_tr_b16 v[192:193], v158 offset:0x9600
	ds_read_b64_tr_b16 v[194:195], v158 offset:0x9e00
	v_max3_f32 v112, v112, v70, v71
	v_add_f32_e32 v115, v65, v115
	v_exp_f32_e32 v69, v69
	v_fmamk_f32 v70, v70, 0x3e0293ee, v114
	v_add_f32_e32 v115, v66, v115
	v_exp_f32_e32 v70, v70
	s_waitcnt lgkmcnt(6)
	v_mfma_f32_32x32x16_bf16 v[48:63], v[168:171], v[180:183], v[48:63]
	ds_read_b64_tr_b16 v[180:181], v158 offset:0xa000
	ds_read_b64_tr_b16 v[182:183], v158 offset:0xa800
	v_fmamk_f32 v71, v71, 0x3e0293ee, v114
	v_max3_f32 v112, v112, v72, v73
	v_add_f32_e32 v115, v67, v115
	v_exp_f32_e32 v71, v71
	v_fmamk_f32 v72, v72, 0x3e0293ee, v114
	v_add_f32_e32 v115, v68, v115
	s_waitcnt lgkmcnt(6)
	v_mfma_f32_32x32x16_bf16 v[32:47], v[168:171], v[184:187], v[32:47]
	ds_read_b64_tr_b16 v[184:185], v158 offset:0xa200
	ds_read_b64_tr_b16 v[186:187], v158 offset:0xaa00
	v_exp_f32_e32 v72, v72
	v_fmamk_f32 v73, v73, 0x3e0293ee, v114
	v_max3_f32 v112, v112, v74, v75
	v_add_f32_e32 v115, v69, v115
	v_exp_f32_e32 v73, v73
	v_fmamk_f32 v74, v74, 0x3e0293ee, v114
	s_waitcnt lgkmcnt(6)
	v_mfma_f32_32x32x16_bf16 v[16:31], v[168:171], v[188:191], v[16:31]
	ds_read_b64_tr_b16 v[188:189], v158 offset:0xa400
	ds_read_b64_tr_b16 v[190:191], v158 offset:0xac00
	v_add_f32_e32 v115, v70, v115
	v_exp_f32_e32 v74, v74
	v_fmamk_f32 v75, v75, 0x3e0293ee, v114
	v_max3_f32 v112, v112, v76, v77
	v_add_f32_e32 v115, v71, v115
	v_exp_f32_e32 v75, v75
	s_waitcnt lgkmcnt(6)
	v_mfma_f32_32x32x16_bf16 v[0:15], v[168:171], v[192:195], v[0:15]
	ds_read_b64_tr_b16 v[192:193], v158 offset:0xa600
	ds_read_b64_tr_b16 v[194:195], v158 offset:0xae00
	v_fmamk_f32 v76, v76, 0x3e0293ee, v114
	v_add_f32_e32 v115, v72, v115
	v_exp_f32_e32 v76, v76
	v_fmamk_f32 v77, v77, 0x3e0293ee, v114
	v_max3_f32 v112, v112, v78, v79
	v_add_f32_e32 v115, v73, v115
	s_waitcnt lgkmcnt(6)
	v_mfma_f32_32x32x16_bf16 v[48:63], v[172:175], v[180:183], v[48:63]
	ds_read_b64_tr_b16 v[180:181], v158 offset:0xb000
	ds_read_b64_tr_b16 v[182:183], v158 offset:0xb800
	v_exp_f32_e32 v77, v77
	v_fmamk_f32 v78, v78, 0x3e0293ee, v114
	v_add_f32_e32 v115, v74, v115
	v_exp_f32_e32 v78, v78
	v_fmac_f32_e32 v114, 0x3e0293ee, v79
	v_add_f32_e32 v115, v75, v115
	s_waitcnt lgkmcnt(6)
	v_mfma_f32_32x32x16_bf16 v[32:47], v[172:175], v[184:187], v[32:47]
	ds_read_b64_tr_b16 v[184:185], v158 offset:0xb200
	ds_read_b64_tr_b16 v[186:187], v158 offset:0xba00
	v_exp_f32_e32 v79, v114
	v_add_f32_e32 v114, v76, v115
	v_mov_b32_e32 v113, v112
	v_add_f32_e32 v114, v77, v114
	s_nop 0
	v_permlane32_swap_b32_e32 v112, v113
	v_add_f32_e32 v114, v78, v114
	s_waitcnt lgkmcnt(6)
	v_mfma_f32_32x32x16_bf16 v[16:31], v[172:175], v[188:191], v[16:31]
	ds_read_b64_tr_b16 v[188:189], v158 offset:0xb400
	ds_read_b64_tr_b16 v[190:191], v158 offset:0xbc00
	v_add_f32_e32 v120, v79, v114
	v_max_f32_e32 v113, v113, v113
	v_max_f32_e32 v112, v112, v112
	v_max_f32_e32 v164, v112, v113
	v_mov_b32_e32 v121, v120
	v_cvt_pk_bf16_f32 v112, v64, v65
	s_waitcnt lgkmcnt(6)
	v_mfma_f32_32x32x16_bf16 v[0:15], v[172:175], v[192:195], v[0:15]
	ds_read_b64_tr_b16 v[192:193], v158 offset:0xb600
	ds_read_b64_tr_b16 v[194:195], v158 offset:0xbe00
	v_cvt_pk_bf16_f32 v113, v66, v67
	v_cvt_pk_bf16_f32 v114, v68, v69
	v_cvt_pk_bf16_f32 v115, v70, v71
	v_cvt_pk_bf16_f32 v116, v72, v73
	v_cvt_pk_bf16_f32 v117, v74, v75
	v_cvt_pk_bf16_f32 v118, v76, v77
	s_waitcnt lgkmcnt(6)
	v_mfma_f32_32x32x16_bf16 v[48:63], v[124:127], v[180:183], v[48:63]
	v_cvt_pk_bf16_f32 v119, v78, v79
	s_nop 1
	v_permlane32_swap_b32_e32 v120, v121
	v_permlane32_swap_b32_e32 v112, v114
	v_permlane32_swap_b32_e32 v113, v115
	v_permlane32_swap_b32_e32 v116, v118
	v_permlane32_swap_b32_e32 v117, v119
	s_waitcnt lgkmcnt(4)
	v_mfma_f32_32x32x16_bf16 v[32:47], v[124:127], v[184:187], v[32:47]
	ds_write_b128 v157, v[112:115]
	ds_write_b128 v157, v[116:119] offset:1024
	v_add_f32_e32 v120, v120, v121
	v_add_f32_e32 v155, v155, v120
	s_waitcnt lgkmcnt(4)
	v_mfma_f32_32x32x16_bf16 v[16:31], v[124:127], v[188:191], v[16:31]
	s_waitcnt lgkmcnt(2)
	v_mfma_f32_32x32x16_bf16 v[0:15], v[124:127], v[192:195], v[0:15]
	s_and_saveexec_b64 s[54:55], s[4:5]
	ds_write_b32 v160, v164 offset:8192
	s_or_b64 exec, exec, s[54:55]
	s_waitcnt vmcnt(0)
	s_waitcnt vmcnt(0) lgkmcnt(0)
	s_barrier
	s_branch .LBB0_733
